# grid barrier: non-last workgroups of an XCD poll the top generation word directly instead of the per-XCD generation word (one release hop less)
# speedup vs baseline: 1.0046x; 1.0021x over previous
.LBB0_46:
	s_or_b64 exec, exec, s[2:3]
	v_cvt_f32_u32_e32 v4, v2
	s_waitcnt vmcnt(0)
	v_readfirstlane_b32 s2, v3
	v_sub_u32_e32 v3, 0, v2
	v_rcp_iflag_f32_e32 v4, v4
	v_add_u32_e32 v5, s2, v1
	v_mul_f32_e32 v4, 0x4f7ffffe, v4
	v_cvt_u32_f32_e32 v4, v4
	v_mul_lo_u32 v1, v3, v4
	v_mul_hi_u32 v1, v4, v1
	v_add_u32_e32 v1, v4, v1
	v_mul_hi_u32 v1, v5, v1
	v_mul_lo_u32 v3, v1, v2
	v_sub_u32_e32 v3, v5, v3
	v_add_u32_e32 v4, 1, v1
	v_cmp_ge_u32_e32 vcc, v3, v2
	s_nop 1
	v_cndmask_b32_e32 v1, v1, v4, vcc
	v_sub_u32_e32 v4, v3, v2
	v_cndmask_b32_e32 v3, v3, v4, vcc
	v_add_u32_e32 v4, 1, v1
	v_cmp_ge_u32_e32 vcc, v3, v2
	v_add_u32_e32 v3, 1, v5
	s_nop 0
	v_cndmask_b32_e32 v1, v1, v4, vcc
	v_mul_lo_u32 v4, v2, v1
	v_add_u32_e32 v2, v4, v2
	v_cmp_ne_u32_e32 vcc, v3, v2
	s_and_saveexec_b64 s[2:3], vcc
	s_xor_b64 s[10:11], exec, s[2:3]
	s_cbranch_execz .LBB0_60
	s_waitcnt lgkmcnt(0)
	s_add_u32 s20, s6, 0x7500
	s_addc_u32 s21, s7, 0
	global_load_dword v0, v113, s[20:21] sc1
	s_waitcnt vmcnt(0)
	v_cmp_eq_u32_e32 vcc, v0, v1
	s_and_saveexec_b64 s[12:13], vcc
	s_cbranch_execz .LBB0_59
	s_add_u32 s16, s6, 0x4200
	s_addc_u32 s17, s7, 0
	s_mov_b32 s2, 1
	s_mov_b64 s[22:23], 0
	s_branch .LBB0_50
